# diff-latent attention loop: K fragments of the second score map and five V fragments read from LDS early into free VGPRs
# speedup vs baseline: 1.0040x; 1.0040x over previous
.LBB0_431:
	s_bitcmp1_b32 s18, 0
	s_cselect_b32 s4, 0x4800, 0
	v_or_b32_e32 v0, s4, v166
	v_add_u32_e32 v210, v0, v171
	ds_read_b128 v[4:7], v210
	ds_read_b128 v[8:11], v210 offset:32
	s_mov_b32 s5, 0xff800000
	s_waitcnt lgkmcnt(1)
	v_mfma_f32_32x32x16_bf16 v[96:111], v[4:7], v[112:115], 0
	ds_read_b128 v[4:7], v210 offset:4608
	s_waitcnt lgkmcnt(1)
	v_mfma_f32_32x32x16_bf16 v[96:111], v[8:11], v[116:119], v[96:111]
	s_waitcnt lgkmcnt(0)
	v_mfma_f32_32x32x16_bf16 v[80:95], v[4:7], v[112:115], 0
	ds_read_b128 v[4:7], v210 offset:4640
	ds_read_b128 v[244:247], v210 offset:64
	ds_read_b128 v[214:217], v210 offset:96
	ds_read_b128 v[228:231], v210 offset:4672
	v_add3_u32 v248, s4, v235, v171
	v_add_u32_e32 v249, 0x3000, v248
	v_add_u32_e32 v248, 0x2000, v248
	ds_read2_b64 v[144:147], v249 offset0:196 offset1:198
	ds_read2_b64 v[148:151], v248 offset0:136 offset1:138
	ds_read2_b64 v[152:155], v249 offset0:200 offset1:202
	ds_read2_b64 v[156:159], v248 offset0:140 offset1:142
	ds_read2_b64 v[160:163], v249 offset0:204 offset1:206
	s_nop 8
	v_max3_f32 v0, v96, s5, v97
	v_max3_f32 v0, v0, v98, v99
	v_max3_f32 v0, v0, v100, v101
	v_max3_f32 v0, v0, v102, v103
	v_max3_f32 v0, v0, v104, v105
	v_max3_f32 v0, v0, v106, v107
	s_waitcnt lgkmcnt(8)
	v_mfma_f32_32x32x16_bf16 v[80:95], v[4:7], v[116:119], v[80:95]
	v_max3_f32 v0, v0, v108, v109
	v_max3_f32 v0, v0, v110, v111
	s_nop 9
	v_max3_f32 v0, v0, v80, v81
	v_max3_f32 v0, v0, v82, v83
	v_max3_f32 v0, v0, v84, v85
	v_max3_f32 v0, v0, v86, v87
	v_max3_f32 v0, v0, v88, v89
	v_max3_f32 v0, v0, v90, v91
	v_max3_f32 v0, v0, v92, v93
	v_max3_f32 v0, v0, v94, v95
	v_mul_f32_e32 v0, 0x3e8293ee, v0
	ds_bpermute_b32 v3, v167, v0
	s_waitcnt lgkmcnt(0)
	v_max3_f32 v0, v2, v0, v3
	v_sub_f32_e32 v3, v2, v0
	v_exp_f32_e32 v14, v3
	v_cmp_neq_f32_e32 vcc, v0, v2
	s_cbranch_vccz .LBB0_433
	v_pk_mul_f32 v[62:63], v[62:63], v[14:15] op_sel_hi:[1,0]
	v_pk_mul_f32 v[60:61], v[60:61], v[14:15] op_sel_hi:[1,0]
	v_pk_mul_f32 v[58:59], v[58:59], v[14:15] op_sel_hi:[1,0]
	v_pk_mul_f32 v[56:57], v[56:57], v[14:15] op_sel_hi:[1,0]
	v_pk_mul_f32 v[54:55], v[54:55], v[14:15] op_sel_hi:[1,0]
	v_pk_mul_f32 v[52:53], v[52:53], v[14:15] op_sel_hi:[1,0]
	v_pk_mul_f32 v[50:51], v[50:51], v[14:15] op_sel_hi:[1,0]
	v_pk_mul_f32 v[48:49], v[48:49], v[14:15] op_sel_hi:[1,0]
	v_pk_mul_f32 v[30:31], v[30:31], v[14:15] op_sel_hi:[1,0]
	v_pk_mul_f32 v[28:29], v[28:29], v[14:15] op_sel_hi:[1,0]
	v_pk_mul_f32 v[26:27], v[26:27], v[14:15] op_sel_hi:[1,0]
	v_pk_mul_f32 v[24:25], v[24:25], v[14:15] op_sel_hi:[1,0]
	v_pk_mul_f32 v[22:23], v[22:23], v[14:15] op_sel_hi:[1,0]
	v_pk_mul_f32 v[20:21], v[20:21], v[14:15] op_sel_hi:[1,0]
	v_pk_mul_f32 v[18:19], v[18:19], v[14:15] op_sel_hi:[1,0]
	v_pk_mul_f32 v[16:17], v[16:17], v[14:15] op_sel_hi:[1,0]
.LBB0_433:
	v_pk_fma_f32 v[2:3], v[96:97], s[58:59], v[0:1] op_sel_hi:[1,0,0] neg_lo:[0,0,1] neg_hi:[0,0,1]
	v_add3_u32 v10, s4, v235, v171
	v_exp_f32_e32 v180, v2
	v_exp_f32_e32 v181, v3
	v_pk_fma_f32 v[2:3], v[98:99], s[58:59], v[0:1] op_sel_hi:[1,0,0] neg_lo:[0,0,1] neg_hi:[0,0,1]
	s_mov_b32 s4, 0xff800000
	v_exp_f32_e32 v178, v2
	v_exp_f32_e32 v179, v3
	v_pk_fma_f32 v[2:3], v[100:101], s[58:59], v[0:1] op_sel_hi:[1,0,0] neg_lo:[0,0,1] neg_hi:[0,0,1]
	s_nop 0
	v_exp_f32_e32 v182, v2
	v_exp_f32_e32 v183, v3
	v_pk_fma_f32 v[2:3], v[102:103], s[58:59], v[0:1] op_sel_hi:[1,0,0] neg_lo:[0,0,1] neg_hi:[0,0,1]
	s_nop 0
	v_exp_f32_e32 v184, v2
	v_exp_f32_e32 v185, v3
	v_pk_fma_f32 v[2:3], v[104:105], s[58:59], v[0:1] op_sel_hi:[1,0,0] neg_lo:[0,0,1] neg_hi:[0,0,1]
	s_nop 0
	v_exp_f32_e32 v186, v2
	v_exp_f32_e32 v187, v3
	v_pk_fma_f32 v[2:3], v[106:107], s[58:59], v[0:1] op_sel_hi:[1,0,0] neg_lo:[0,0,1] neg_hi:[0,0,1]
	s_nop 0
	v_exp_f32_e32 v188, v2
	v_exp_f32_e32 v189, v3
	v_pk_fma_f32 v[2:3], v[108:109], s[58:59], v[0:1] op_sel_hi:[1,0,0] neg_lo:[0,0,1] neg_hi:[0,0,1]
	s_nop 0
	v_exp_f32_e32 v194, v2
	v_exp_f32_e32 v195, v3
	v_pk_fma_f32 v[2:3], v[110:111], s[58:59], v[0:1] op_sel_hi:[1,0,0] neg_lo:[0,0,1] neg_hi:[0,0,1]
	s_nop 0
	v_exp_f32_e32 v200, v2
	v_exp_f32_e32 v201, v3
	v_pk_fma_f32 v[2:3], v[80:81], s[58:59], v[0:1] op_sel_hi:[1,0,0] neg_lo:[0,0,1] neg_hi:[0,0,1]
	v_cvt_pk_bf16_f32 v80, v180, v181
	v_exp_f32_e32 v198, v2
	v_exp_f32_e32 v199, v3
	v_pk_fma_f32 v[2:3], v[82:83], s[58:59], v[0:1] op_sel_hi:[1,0,0] neg_lo:[0,0,1] neg_hi:[0,0,1]
	v_cvt_pk_bf16_f32 v81, v178, v179
	v_exp_f32_e32 v204, v2
	v_exp_f32_e32 v205, v3
	v_pk_fma_f32 v[2:3], v[84:85], s[58:59], v[0:1] op_sel_hi:[1,0,0] neg_lo:[0,0,1] neg_hi:[0,0,1]
	v_add_u32_e32 v84, 0x2000, v10
	v_exp_f32_e32 v208, v2
	v_exp_f32_e32 v209, v3
	v_pk_fma_f32 v[2:3], v[86:87], s[58:59], v[0:1] op_sel_hi:[1,0,0] neg_lo:[0,0,1] neg_hi:[0,0,1]
	v_add_u32_e32 v85, 0x3000, v10
	v_exp_f32_e32 v190, v2
	v_exp_f32_e32 v191, v3
	v_pk_fma_f32 v[2:3], v[88:89], s[58:59], v[0:1] op_sel_hi:[1,0,0] neg_lo:[0,0,1] neg_hi:[0,0,1]
	v_cvt_pk_bf16_f32 v82, v182, v183
	v_exp_f32_e32 v192, v2
	v_exp_f32_e32 v193, v3
	v_pk_fma_f32 v[2:3], v[90:91], s[58:59], v[0:1] op_sel_hi:[1,0,0] neg_lo:[0,0,1] neg_hi:[0,0,1]
	v_cvt_pk_bf16_f32 v83, v184, v185
	v_exp_f32_e32 v196, v2
	v_exp_f32_e32 v197, v3
	v_pk_fma_f32 v[2:3], v[92:93], s[58:59], v[0:1] op_sel_hi:[1,0,0] neg_lo:[0,0,1] neg_hi:[0,0,1]
	s_nop 0
	v_exp_f32_e32 v202, v2
	v_exp_f32_e32 v203, v3
	v_pk_fma_f32 v[2:3], v[94:95], s[58:59], v[0:1] op_sel_hi:[1,0,0] neg_lo:[0,0,1] neg_hi:[0,0,1]
	s_nop 0
	v_exp_f32_e32 v206, v2
	v_exp_f32_e32 v207, v3
	ds_read2_b64 v[6:9], v84 offset0:128 offset1:130
	ds_read2_b64 v[2:5], v84 offset0:132 offset1:134
	ds_read2_b64 v[10:13], v85 offset0:192 offset1:194
	s_waitcnt lgkmcnt(2)
	v_mfma_f32_32x32x16_bf16 v[48:63], v[6:9], v[80:83], v[48:63]
	s_waitcnt lgkmcnt(0)
	v_mfma_f32_32x32x16_bf16 v[16:31], v[10:13], v[80:83], v[16:31]
	v_cvt_pk_bf16_f32 v80, v186, v187
	v_cvt_pk_bf16_f32 v81, v188, v189
	v_cvt_pk_bf16_f32 v82, v194, v195
	v_cvt_pk_bf16_f32 v83, v200, v201
	s_nop 1
	v_mfma_f32_32x32x16_bf16 v[48:63], v[2:5], v[80:83], v[48:63]
	s_waitcnt lgkmcnt(4)
	v_mfma_f32_32x32x16_bf16 v[16:31], v[144:147], v[80:83], v[16:31]
	v_cvt_pk_bf16_f32 v80, v198, v199
	v_cvt_pk_bf16_f32 v81, v204, v205
	v_cvt_pk_bf16_f32 v82, v208, v209
	v_cvt_pk_bf16_f32 v83, v190, v191
	s_waitcnt lgkmcnt(3)
	s_nop 0
	v_mfma_f32_32x32x16_bf16 v[48:63], v[148:151], v[80:83], v[48:63]
	s_waitcnt lgkmcnt(2)
	v_mfma_f32_32x32x16_bf16 v[16:31], v[152:155], v[80:83], v[16:31]
	v_cvt_pk_bf16_f32 v80, v192, v193
	v_cvt_pk_bf16_f32 v81, v196, v197
	v_cvt_pk_bf16_f32 v82, v202, v203
	v_cvt_pk_bf16_f32 v83, v206, v207
	s_waitcnt lgkmcnt(1)
	s_nop 0
	v_mfma_f32_32x32x16_bf16 v[48:63], v[156:159], v[80:83], v[48:63]
	s_waitcnt lgkmcnt(0)
	v_mfma_f32_32x32x16_bf16 v[16:31], v[160:163], v[80:83], v[16:31]
	ds_read_b128 v[238:241], v210 offset:4704
	v_mfma_f32_32x32x16_bf16 v[96:111], v[244:247], v[120:123], 0
	v_mfma_f32_32x32x16_bf16 v[96:111], v[214:217], v[124:127], v[96:111]
	v_mfma_f32_32x32x16_bf16 v[80:95], v[228:231], v[120:123], 0
	s_nop 10
	v_max3_f32 v210, v96, s4, v97
	v_max3_f32 v210, v210, v98, v99
	v_max3_f32 v210, v210, v100, v101
	v_max3_f32 v210, v210, v102, v103
	v_max3_f32 v210, v210, v104, v105
	v_max3_f32 v210, v210, v106, v107
	v_max3_f32 v210, v210, v108, v109
	s_waitcnt lgkmcnt(0)
	v_mfma_f32_32x32x16_bf16 v[80:95], v[238:241], v[124:127], v[80:95]
	v_max3_f32 v210, v210, v110, v111
	s_nop 10
	v_max3_f32 v210, v210, v80, v81
	v_max3_f32 v210, v210, v82, v83
	v_max3_f32 v210, v210, v84, v85
	v_max3_f32 v210, v210, v86, v87
	v_max3_f32 v210, v210, v88, v89
	v_max3_f32 v210, v210, v90, v91
	v_max3_f32 v210, v210, v92, v93
	v_max3_f32 v210, v210, v94, v95
	v_mul_f32_e32 v210, 0x3e8293ee, v210
	ds_bpermute_b32 v211, v167, v210
	s_waitcnt lgkmcnt(0)
	v_max3_f32 v210, v237, v210, v211
	v_sub_f32_e32 v211, v237, v210
	v_exp_f32_e32 v212, v211
	v_cmp_neq_f32_e32 vcc, v210, v237
	s_cbranch_vccz .LBB0_435
	v_pk_mul_f32 v[78:79], v[78:79], v[212:213] op_sel_hi:[1,0]
	v_pk_mul_f32 v[76:77], v[76:77], v[212:213] op_sel_hi:[1,0]
	v_pk_mul_f32 v[74:75], v[74:75], v[212:213] op_sel_hi:[1,0]
	v_pk_mul_f32 v[72:73], v[72:73], v[212:213] op_sel_hi:[1,0]
	v_pk_mul_f32 v[70:71], v[70:71], v[212:213] op_sel_hi:[1,0]
	v_pk_mul_f32 v[68:69], v[68:69], v[212:213] op_sel_hi:[1,0]
	v_pk_mul_f32 v[66:67], v[66:67], v[212:213] op_sel_hi:[1,0]
	v_pk_mul_f32 v[64:65], v[64:65], v[212:213] op_sel_hi:[1,0]
	v_pk_mul_f32 v[46:47], v[46:47], v[212:213] op_sel_hi:[1,0]
	v_pk_mul_f32 v[44:45], v[44:45], v[212:213] op_sel_hi:[1,0]
	v_pk_mul_f32 v[42:43], v[42:43], v[212:213] op_sel_hi:[1,0]
	v_pk_mul_f32 v[40:41], v[40:41], v[212:213] op_sel_hi:[1,0]
	v_pk_mul_f32 v[38:39], v[38:39], v[212:213] op_sel_hi:[1,0]
	v_pk_mul_f32 v[36:37], v[36:37], v[212:213] op_sel_hi:[1,0]
	v_pk_mul_f32 v[34:35], v[34:35], v[212:213] op_sel_hi:[1,0]
	v_pk_mul_f32 v[32:33], v[32:33], v[212:213] op_sel_hi:[1,0]
